# v14 + cross-half max via v_permlane32_swap + rotated NSA tile loop: staging right after QK issue, per-tile barrier before exp/PV, next tile's K/V fragments prefetched behind PV
# speedup vs baseline: 1.0055x; 1.0007x over previous
; #define LAS __attribute__((address_space(3)))
; DI f32x16 mma32(bf16x8 a, bf16x8 b, f32x16 c) { return __builtin_amdgcn_mfma_f32_32x32x16_bf16(a, b, c, 0, 0, 0); }
; DI int crow(int i, int hf) { return (i & 3) + 8 * (i >> 2) + 4 * hf; }
; DI void nsa_item(KA a, LAS unsigned char* lds, const int it) {
;     ...
;         of[0] = ot[0] * g0; of[1] = ot[1] * g0;
;     ...
;     float m_ref = 0.f, l_run = 0.f; f32x16 ot[2] = {ZERO16, ZERO16}; int curtype = 0;
;     for (int i = 0; i < n; ++i) {
;         const int desc = LIST[i]; const int ty = desc >> 8, j = desc & 255;
;         const LAS bf16* Kc = (i & 1) ? Kt1 : Kt; const LAS bf16* Vc = (i & 1) ? VT1 : VT;
;         if (ty != curtype) { const float lt = l_run + __shfl_xor(l_run, 32); const float sc = g1 / lt; of[0] += ot[0] * sc; of[1] += ot[1] * sc; ot[0] = ZERO16; ot[1] = ZERO16; m_ref = 0.f; l_run = 0.f; curtype = ty; }
;         const bool rowoff = (ty == 0) && (((mysel >> j) & 1u) == 0u);
;         const int mode = (j == qb) ? 1 : ((ty == 1 && j == qb - 8) ? 2 : 0);
;         const float init = rowoff ? -INFINITY : -m_ref;
;         f32x16 st[2];
; #pragma unroll
;         for (int i2 = 0; i2 < 16; ++i2) { st[0][i2] = init; st[1][i2] = init; }
; #pragma unroll
;         for (int kt = 0; kt < 2; ++kt)
; #pragma unroll
;             for (int s = 0; s < 4; ++s) { const bf16x8 af = *(const LAS bf16x8*)(Kc + (32 * kt + r) * PA + 16 * s + 8 * hf); st[kt] = mma32(af, bq[s], st[kt]); }
;         if (mode != 0) {
; #pragma unroll
;             for (int kt = 0; kt < 2; ++kt)
; #pragma unroll
;                 for (int i2 = 0; i2 < 16; ++i2) { const int kl = 32 * kt + crow(i2, hf); const bool bad = rowoff || (mode == 1 && kl > tql) || (mode == 2 && kl <= tql); st[kt][i2] = bad ? -INFINITY : st[kt][i2]; }
.LBB0_794:
	v_add_f32_e32 v33, 1.0, v33
	v_rcp_f32_e32 v34, v33
	s_andn2_b64 vcc, exec, s[0:1]
	v_readlane_b32 s90, v254, 47
	v_pk_mul_f32 v[124:125], v[34:35], v[30:31] op_sel_hi:[0,1]
	v_pk_mul_f32 v[120:121], v[34:35], v[28:29] op_sel_hi:[0,1]
	v_pk_mul_f32 v[116:117], v[34:35], v[26:27] op_sel_hi:[0,1]
	v_pk_mul_f32 v[112:113], v[34:35], v[24:25] op_sel_hi:[0,1]
	v_pk_mul_f32 v[108:109], v[34:35], v[22:23] op_sel_hi:[0,1]
	v_pk_mul_f32 v[104:105], v[34:35], v[20:21] op_sel_hi:[0,1]
	v_pk_mul_f32 v[100:101], v[34:35], v[18:19] op_sel_hi:[0,1]
	v_pk_mul_f32 v[96:97], v[34:35], v[16:17] op_sel_hi:[0,1]
	v_pk_mul_f32 v[122:123], v[34:35], v[14:15] op_sel_hi:[0,1]
	v_pk_mul_f32 v[118:119], v[34:35], v[12:13] op_sel_hi:[0,1]
	v_pk_mul_f32 v[114:115], v[34:35], v[10:11] op_sel_hi:[0,1]
	v_pk_mul_f32 v[110:111], v[34:35], v[8:9] op_sel_hi:[0,1]
	v_pk_mul_f32 v[106:107], v[34:35], v[6:7] op_sel_hi:[0,1]
	v_pk_mul_f32 v[102:103], v[34:35], v[4:5] op_sel_hi:[0,1]
	v_pk_mul_f32 v[98:99], v[34:35], v[2:3] op_sel_hi:[0,1]
	v_pk_mul_f32 v[94:95], v[34:35], v[0:1] op_sel_hi:[0,1]
	v_mov_b32_e32 v31, 0
	s_cbranch_vccnz .LBB0_811
	v_cmp_gt_u32_e64 s[0:1], v92, v135
	v_or_b32_e32 v0, 2, v92
	s_sub_i32 s85, 23, s40
	v_writelane_b32 v254, s0, 49
	s_mov_b32 s87, 0
	s_mov_b32 s88, 0
	v_writelane_b32 v254, s1, 50
	v_cmp_le_u32_e64 s[0:1], v92, v135
	v_mov_b32_e32 v137, 0
	v_mov_b32_e32 v16, 0
	v_writelane_b32 v254, s0, 51
	s_nop 1
	v_writelane_b32 v254, s1, 52
	v_cmp_ge_u32_e64 s[0:1], v92, v135
	s_nop 1
	v_writelane_b32 v254, s0, 53
	s_nop 1
	v_writelane_b32 v254, s1, 54
	v_cmp_lt_u32_e64 s[0:1], v92, v135
	s_nop 1
	v_writelane_b32 v254, s0, 55
	s_nop 1
	v_writelane_b32 v254, s1, 56
	v_cmp_gt_u32_e64 s[0:1], v0, v135
	s_nop 1
	v_writelane_b32 v254, s0, 57
	s_nop 1
	v_writelane_b32 v254, s1, 58
	v_cmp_le_u32_e64 s[0:1], v0, v135
	v_or_b32_e32 v0, 3, v92
	s_nop 0
	v_writelane_b32 v254, s0, 59
	s_nop 1
	v_writelane_b32 v254, s1, 60
	v_cmp_gt_u32_e64 s[0:1], v0, v135
	s_nop 1
	v_writelane_b32 v254, s0, 61
	s_nop 1
	v_writelane_b32 v254, s1, 62
	v_cmp_le_u32_e64 s[0:1], v0, v135
	v_or_b32_e32 v0, 8, v92
	s_nop 0
	v_writelane_b32 v254, s0, 63
	s_nop 0
	v_readlane_b32 s86, v254, 13
	v_writelane_b32 v245, s1, 0
	v_cmp_gt_u32_e64 s[0:1], v0, v135
	s_nop 1
	v_writelane_b32 v245, s0, 1
	s_nop 1
	v_writelane_b32 v245, s1, 2
	v_cmp_le_u32_e64 s[0:1], v0, v135
	v_or_b32_e32 v0, 9, v92
	s_nop 0
	v_writelane_b32 v245, s0, 3
	s_nop 1
	v_writelane_b32 v245, s1, 4
	v_cmp_gt_u32_e64 s[0:1], v0, v135
	s_nop 1
	v_writelane_b32 v245, s0, 5
	s_nop 1
	v_writelane_b32 v245, s1, 6
	v_cmp_le_u32_e64 s[0:1], v0, v135
	v_or_b32_e32 v0, 10, v92
	s_nop 0
	v_writelane_b32 v245, s0, 7
	s_nop 1
	v_writelane_b32 v245, s1, 8
	v_cmp_gt_u32_e64 s[0:1], v0, v135
	s_nop 1
	v_writelane_b32 v245, s0, 9
	s_nop 1
	v_writelane_b32 v245, s1, 10
	v_cmp_le_u32_e64 s[0:1], v0, v135
	v_or_b32_e32 v0, 11, v92
	s_nop 0
	v_writelane_b32 v245, s0, 11
	s_nop 1
	v_writelane_b32 v245, s1, 12
	v_cmp_gt_u32_e64 s[0:1], v0, v135
	s_nop 1
	v_writelane_b32 v245, s0, 13
	s_nop 1
	v_writelane_b32 v245, s1, 14
	v_cmp_le_u32_e64 s[0:1], v0, v135
	v_or_b32_e32 v0, 16, v92
	s_nop 0
	v_writelane_b32 v245, s0, 15
	s_nop 1
	v_writelane_b32 v245, s1, 16
	v_cmp_gt_u32_e64 s[0:1], v0, v135
	s_nop 1
	v_writelane_b32 v245, s0, 17
	s_nop 1
	v_writelane_b32 v245, s1, 18
	v_cmp_le_u32_e64 s[0:1], v0, v135
	v_or_b32_e32 v0, 17, v92
	s_nop 0
	v_writelane_b32 v245, s0, 19
	s_nop 1
	v_writelane_b32 v245, s1, 20
	v_cmp_gt_u32_e64 s[0:1], v0, v135
	s_nop 1
	v_writelane_b32 v245, s0, 21
	s_nop 1
	v_writelane_b32 v245, s1, 22
	v_cmp_le_u32_e64 s[0:1], v0, v135
	v_or_b32_e32 v0, 18, v92
	s_nop 0
	v_writelane_b32 v245, s0, 23
	s_nop 1
	v_writelane_b32 v245, s1, 24
	v_cmp_gt_u32_e64 s[0:1], v0, v135
	s_nop 1
	v_writelane_b32 v245, s0, 25
	s_nop 1
	v_writelane_b32 v245, s1, 26
	v_cmp_le_u32_e64 s[0:1], v0, v135
	v_or_b32_e32 v0, 19, v92
	s_nop 0
	v_writelane_b32 v245, s0, 27
	s_nop 1
	v_writelane_b32 v245, s1, 28
	v_cmp_gt_u32_e64 s[0:1], v0, v135
	s_nop 1
	v_writelane_b32 v245, s0, 29
	s_nop 1
	v_writelane_b32 v245, s1, 30
	v_cmp_le_u32_e64 s[0:1], v0, v135
	v_or_b32_e32 v0, 24, v92
	s_nop 0
	v_writelane_b32 v245, s0, 31
	s_nop 1
	v_writelane_b32 v245, s1, 32
	v_cmp_gt_u32_e64 s[0:1], v0, v135
	s_nop 1
	v_writelane_b32 v245, s0, 33
	s_nop 1
	v_writelane_b32 v245, s1, 34
	v_cmp_le_u32_e64 s[0:1], v0, v135
	v_or_b32_e32 v0, 25, v92
	v_cmp_gt_u32_e64 s[92:93], v0, v135
	v_cmp_le_u32_e64 s[94:95], v0, v135
	v_or_b32_e32 v0, 26, v92
	v_cmp_gt_u32_e64 s[96:97], v0, v135
	v_cmp_le_u32_e64 s[6:7], v0, v135
	v_or_b32_e32 v0, 27, v92
	v_cmp_gt_u32_e64 s[8:9], v0, v135
	v_cmp_le_u32_e64 s[10:11], v0, v135
	v_or_b32_e32 v0, 32, v92
	v_cmp_gt_u32_e64 s[12:13], v0, v135
	v_cmp_le_u32_e64 s[14:15], v0, v135
	v_or_b32_e32 v0, 33, v92
	v_cmp_gt_u32_e64 s[16:17], v0, v135
	v_cmp_le_u32_e64 s[18:19], v0, v135
	v_or_b32_e32 v0, 34, v92
	v_cmp_gt_u32_e64 s[20:21], v0, v135
	v_cmp_le_u32_e64 s[22:23], v0, v135
	v_or_b32_e32 v0, 35, v92
	v_cmp_gt_u32_e64 s[24:25], v0, v135
	v_cmp_le_u32_e64 s[26:27], v0, v135
	v_or_b32_e32 v0, 40, v92
	v_cmp_gt_u32_e64 s[28:29], v0, v135
	v_cmp_le_u32_e64 s[30:31], v0, v135
	v_or_b32_e32 v0, 41, v92
	v_cmp_gt_u32_e64 s[34:35], v0, v135
	v_cmp_le_u32_e64 s[36:37], v0, v135
	v_or_b32_e32 v0, 42, v92
	v_cmp_gt_u32_e64 s[38:39], v0, v135
	v_cmp_le_u32_e64 s[4:5], v0, v135
	v_or_b32_e32 v0, 43, v92
	v_writelane_b32 v245, s0, 35
	v_cmp_gt_u32_e64 s[40:41], v0, v135
	v_cmp_le_u32_e64 s[2:3], v0, v135
	v_or_b32_e32 v0, 48, v92
	v_writelane_b32 v245, s1, 36
	v_cmp_gt_u32_e64 s[0:1], v0, v135
	v_cmp_le_u32_e64 s[42:43], v0, v135
; #define LAS __attribute__((address_space(3)))
; DI f32x16 mma32(bf16x8 a, bf16x8 b, f32x16 c) { return __builtin_amdgcn_mfma_f32_32x32x16_bf16(a, b, c, 0, 0, 0); }
; #define NSA_STORE(Kb, Vb) do { *(LAS v4u*)((Kb) + skey * PA + 8 * sch) = kreg; LAS unsigned* d0_ = (LAS unsigned*)((Vb) + (4 * sdg) * PV + vpos(2 * skp)); \
;         d0_[0] = (vr0.x & 0xffffu) | (vr1.x << 16); d0_[PV / 2] = (vr0.x >> 16) | (vr1.x & 0xffff0000u); d0_[PV] = (vr0.y & 0xffffu) | (vr1.y << 16); d0_[3 * PV / 2] = (vr0.y >> 16) | (vr1.y & 0xffff0000u); } while (0)
; DI void nsa_item(KA a, LAS unsigned char* lds, const int it) {
;     ...
;     const unsigned mysel = SELM[tql]; const int n = *NLIST;
;     LAS bf16* Kt1 = (LAS bf16*)(lds + NSA_KT1); LAS bf16* VT1 = (LAS bf16*)(lds + NSA_VT1);
;     NSA_STORE(Kt, VT);
;     NSA_LOAD(LIST[1]);
;     __syncthreads();
;     float m_ref = 0.f, l_run = 0.f; f32x16 ot[2] = {ZERO16, ZERO16}; int curtype = 0;
;     for (int i = 0; i < n; ++i) {
;         const int desc = LIST[i]; const int ty = desc >> 8, j = desc & 255;
;         const LAS bf16* Kc = (i & 1) ? Kt1 : Kt; const LAS bf16* Vc = (i & 1) ? VT1 : VT;
;         if (ty != curtype) { const float lt = l_run + __shfl_xor(l_run, 32); const float sc = g1 / lt; of[0] += ot[0] * sc; of[1] += ot[1] * sc; ot[0] = ZERO16; ot[1] = ZERO16; m_ref = 0.f; l_run = 0.f; curtype = ty; }
;         const bool rowoff = (ty == 0) && (((mysel >> j) & 1u) == 0u);
;         const int mode = (j == qb) ? 1 : ((ty == 1 && j == qb - 8) ? 2 : 0);
;         const float init = rowoff ? -INFINITY : -m_ref;
;         f32x16 st[2];
; #pragma unroll
;         for (int i2 = 0; i2 < 16; ++i2) { st[0][i2] = init; st[1][i2] = init; }
; #pragma unroll
;         for (int kt = 0; kt < 2; ++kt)
; #pragma unroll
;             for (int s = 0; s < 4; ++s) { const bf16x8 af = *(const LAS bf16x8*)(Kc + (32 * kt + r) * PA + 16 * s + 8 * hf); st[kt] = mma32(af, bq[s], st[kt]); }
	v_or_b32_e32 v0, 49, v92
	v_cmp_gt_u32_e64 s[44:45], v0, v135
	v_cmp_le_u32_e64 s[46:47], v0, v135
	v_or_b32_e32 v0, 50, v92
	v_cmp_gt_u32_e64 s[48:49], v0, v135
	v_cmp_le_u32_e64 s[50:51], v0, v135
	v_or_b32_e32 v0, 51, v92
	v_cmp_gt_u32_e64 s[52:53], v0, v135
	v_cmp_le_u32_e64 s[54:55], v0, v135
	v_or_b32_e32 v0, 56, v92
	v_cmp_gt_u32_e64 s[56:57], v0, v135
	v_cmp_le_u32_e64 s[58:59], v0, v135
	v_or_b32_e32 v0, 57, v92
	v_cmp_gt_u32_e64 s[60:61], v0, v135
	v_cmp_le_u32_e64 s[62:63], v0, v135
	v_or_b32_e32 v0, 58, v92
	v_cmp_gt_u32_e64 s[64:65], v0, v135
	v_cmp_le_u32_e64 s[66:67], v0, v135
	v_or_b32_e32 v0, 59, v92
	v_cmp_gt_u32_e64 s[68:69], v0, v135
	v_cmp_le_u32_e64 s[70:71], v0, v135
	v_mov_b32_e32 v135, 0
	v_mov_b32_e32 v0, 0
	v_mov_b32_e32 v1, v135
	v_mov_b32_e32 v2, v135
	v_mov_b32_e32 v3, v135
	v_mov_b32_e32 v4, v135
	v_mov_b32_e32 v5, v135
	v_mov_b32_e32 v6, v135
	v_mov_b32_e32 v7, v135
	v_mov_b32_e32 v8, v135
	v_mov_b32_e32 v9, v135
	v_mov_b32_e32 v10, v135
	v_mov_b32_e32 v11, v135
	v_mov_b32_e32 v12, v135
	v_mov_b32_e32 v13, v135
	v_mov_b32_e32 v14, v135
	v_mov_b32_e32 v15, v135
	v_mov_b32_e32 v17, v135
	v_mov_b32_e32 v18, v135
	v_mov_b32_e32 v19, v135
	v_mov_b32_e32 v20, v135
	v_mov_b32_e32 v21, v135
	v_mov_b32_e32 v22, v135
	v_mov_b32_e32 v23, v135
	v_mov_b32_e32 v24, v135
	v_mov_b32_e32 v25, v135
	v_mov_b32_e32 v26, v135
	v_mov_b32_e32 v27, v135
	v_mov_b32_e32 v28, v135
	v_mov_b32_e32 v29, v135
	v_mov_b32_e32 v30, v135
	v_mov_b32_e32 v31, v135
	v_add3_u32 v231, 0, v90, v130
	s_movk_i32 s74, 0x4800
	v_add3_u32 v230, s74, v90, v131
	ds_read_b128 v[170:173], v231 offset:64
	ds_read_b128 v[178:181], v231 offset:4608
	ds_read_b128 v[182:185], v231 offset:4640
	ds_read_b128 v[186:189], v231 offset:4672
	ds_read_b128 v[206:209], v231 offset:4704
	ds_read_b128 v[174:177], v231 offset:96
	s_add_i32 s74, s86, -8
	v_mov_b32_e32 v191, s74
	ds_read_b32 v191, v191
	v_mov_b32_e32 v250, s86
	ds_read_b32 v250, v250
	ds_read_b128 v[210:213], v230
	ds_read_b128 v[218:221], v230 offset:8704
	ds_read_b128 v[222:225], v230 offset:8736
	ds_read_b128 v[214:217], v230 offset:32
	ds_read_b128 v[226:229], v230 offset:64
	ds_read_b128 v[152:155], v230 offset:8768
	ds_read_b128 v[246:249], v230 offset:96
	ds_read_b128 v[144:147], v231
	ds_read_b128 v[148:151], v231 offset:32
.LBB0_796:
	s_waitcnt lgkmcnt(10)
	v_readfirstlane_b32 s78, v191
	s_ashr_i32 s82, s78, 8
	s_cmp_eq_u32 s82, s88
	s_cbranch_scc1 .LBB0_798
	ds_bpermute_b32 v32, v134, v135
	v_mov_b32_e32 v137, 0
	s_mov_b32 s88, s82
	s_waitcnt lgkmcnt(0)
	v_add_f32_e32 v32, v135, v32
	v_div_scale_f32 v33, s[74:75], v32, v32, v93
	v_rcp_f32_e32 v34, v33
	v_div_scale_f32 v35, vcc, v93, v32, v93
	v_mov_b32_e32 v135, 0
	v_fma_f32 v36, -v33, v34, 1.0
	v_fmac_f32_e32 v34, v36, v34
	v_mul_f32_e32 v36, v35, v34
	v_fma_f32 v37, -v33, v36, v35
	v_fmac_f32_e32 v36, v37, v34
	v_fma_f32 v33, -v33, v36, v35
	v_div_fmas_f32 v33, v33, v34, v36
	v_div_fixup_f32 v32, v33, v32, v93
	v_pk_fma_f32 v[124:125], v[30:31], v[32:33], v[124:125] op_sel_hi:[1,0,1]
	v_pk_fma_f32 v[120:121], v[28:29], v[32:33], v[120:121] op_sel_hi:[1,0,1]
	v_pk_fma_f32 v[116:117], v[26:27], v[32:33], v[116:117] op_sel_hi:[1,0,1]
	v_pk_fma_f32 v[112:113], v[24:25], v[32:33], v[112:113] op_sel_hi:[1,0,1]
	v_pk_fma_f32 v[108:109], v[22:23], v[32:33], v[108:109] op_sel_hi:[1,0,1]
	v_pk_fma_f32 v[104:105], v[20:21], v[32:33], v[104:105] op_sel_hi:[1,0,1]
	v_pk_fma_f32 v[100:101], v[18:19], v[32:33], v[100:101] op_sel_hi:[1,0,1]
	v_pk_fma_f32 v[96:97], v[16:17], v[32:33], v[96:97] op_sel_hi:[1,0,1]
	v_pk_fma_f32 v[122:123], v[14:15], v[32:33], v[122:123] op_sel_hi:[1,0,1]
	v_pk_fma_f32 v[118:119], v[12:13], v[32:33], v[118:119] op_sel_hi:[1,0,1]
	v_pk_fma_f32 v[114:115], v[10:11], v[32:33], v[114:115] op_sel_hi:[1,0,1]
	v_pk_fma_f32 v[110:111], v[8:9], v[32:33], v[110:111] op_sel_hi:[1,0,1]
	v_pk_fma_f32 v[106:107], v[6:7], v[32:33], v[106:107] op_sel_hi:[1,0,1]
	v_pk_fma_f32 v[102:103], v[4:5], v[32:33], v[102:103] op_sel_hi:[1,0,1]
	v_pk_fma_f32 v[98:99], v[2:3], v[32:33], v[98:99] op_sel_hi:[1,0,1]
	v_pk_fma_f32 v[94:95], v[0:1], v[32:33], v[94:95] op_sel_hi:[1,0,1]
	v_mov_b32_e32 v0, 0
	v_mov_b32_e32 v1, v137
	v_mov_b32_e32 v2, v137
	v_mov_b32_e32 v3, v137
	v_mov_b32_e32 v4, v137
	v_mov_b32_e32 v5, v137
	v_mov_b32_e32 v6, v137
	v_mov_b32_e32 v7, v137
	v_mov_b32_e32 v8, v137
	v_mov_b32_e32 v9, v137
	v_mov_b32_e32 v10, v137
	v_mov_b32_e32 v11, v137
	v_mov_b32_e32 v12, v137
	v_mov_b32_e32 v13, v137
	v_mov_b32_e32 v14, v137
	v_mov_b32_e32 v15, v137
	v_mov_b32_e32 v16, 0
	v_mov_b32_e32 v17, v137
	v_mov_b32_e32 v18, v137
	v_mov_b32_e32 v19, v137
	v_mov_b32_e32 v20, v137
	v_mov_b32_e32 v21, v137
	v_mov_b32_e32 v22, v137
	v_mov_b32_e32 v23, v137
	v_mov_b32_e32 v24, v137
	v_mov_b32_e32 v25, v137
	v_mov_b32_e32 v26, v137
	v_mov_b32_e32 v27, v137
	v_mov_b32_e32 v28, v137
	v_mov_b32_e32 v29, v137
	v_mov_b32_e32 v30, v137
	v_mov_b32_e32 v31, v137
; #define LAS __attribute__((address_space(3)))
; DI f32x16 mma32(bf16x8 a, bf16x8 b, f32x16 c) { return __builtin_amdgcn_mfma_f32_32x32x16_bf16(a, b, c, 0, 0, 0); }
; DI int crow(int i, int hf) { return (i & 3) + 8 * (i >> 2) + 4 * hf; }
; DI void nsa_item(KA a, LAS unsigned char* lds, const int it) {
;     ...
;         const bool rowoff = (ty == 0) && (((mysel >> j) & 1u) == 0u);
;         const int mode = (j == qb) ? 1 : ((ty == 1 && j == qb - 8) ? 2 : 0);
;         const float init = rowoff ? -INFINITY : -m_ref;
;         f32x16 st[2];
; #pragma unroll
;         for (int i2 = 0; i2 < 16; ++i2) { st[0][i2] = init; st[1][i2] = init; }
; #pragma unroll
;         for (int kt = 0; kt < 2; ++kt)
; #pragma unroll
;             for (int s = 0; s < 4; ++s) { const bf16x8 af = *(const LAS bf16x8*)(Kc + (32 * kt + r) * PA + 16 * s + 8 * hf); st[kt] = mma32(af, bq[s], st[kt]); }
;         if (mode != 0) {
; #pragma unroll
;             for (int kt = 0; kt < 2; ++kt)
; #pragma unroll
;                 for (int i2 = 0; i2 < 16; ++i2) { const int kl = 32 * kt + crow(i2, hf); const bool bad = rowoff || (mode == 1 && kl > tql) || (mode == 2 && kl <= tql); st[kt][i2] = bad ? -INFINITY : st[kt][i2]; }
.LBB0_798:
	s_and_b32 s83, s78, 0xff
	s_and_b32 s76, s87, 1
	s_bitcmp1_b32 s87, 0
	s_cselect_b64 s[74:75], -1, 0
	s_cmp_eq_u32 s76, 0
	s_cselect_b64 s[76:77], -1, 0
	s_and_b64 s[80:81], s[76:77], exec
	v_readlane_b32 s79, v254, 14
	s_cselect_b32 s89, 0, s79
	v_add3_u32 v89, s89, v90, v130
	s_cmpk_lt_u32 s78, 0x100
	s_cselect_b64 s[80:81], -1, 0
	s_lshl_b32 s78, 1, s78
	v_and_b32_e32 v32, s78, v141
	v_cmp_eq_u32_e32 vcc, 0, v32
	s_and_b64 s[78:79], s[80:81], vcc
	v_cndmask_b32_e64 v32, -v137, v240, s[78:79]
	v_mov_b32_e32 v33, v32
	v_mov_b32_e32 v34, v32
	v_mov_b32_e32 v35, v32
	v_mov_b32_e32 v36, v32
	v_mov_b32_e32 v37, v32
	v_mov_b32_e32 v38, v32
	v_mov_b32_e32 v39, v32
	v_mov_b32_e32 v40, v32
	v_mov_b32_e32 v41, v32
	v_mov_b32_e32 v42, v32
	v_mov_b32_e32 v43, v32
	v_mov_b32_e32 v44, v32
	v_mov_b32_e32 v45, v32
	v_mov_b32_e32 v46, v32
	v_mov_b32_e32 v47, v32
	s_cmp_eq_u32 s83, s90
	s_cselect_b64 s[80:81], -1, 0
	s_nop 0
	v_mfma_f32_32x32x16_bf16 v[48:63], v[170:173], v[68:71], v[32:47]
	s_cmp_eq_u32 s83, s85
	s_cselect_b64 vcc, -1, 0
	s_cmp_eq_u32 s82, 1
	s_cselect_b64 s[82:83], -1, 0
	s_and_b64 s[82:83], s[82:83], vcc
	s_or_b64 vcc, s[80:81], s[82:83]
	s_andn2_b64 vcc, exec, vcc
	v_mfma_f32_32x32x16_bf16 v[32:47], v[178:181], v[72:75], v[32:47]
	v_mfma_f32_32x32x16_bf16 v[32:47], v[182:185], v[64:67], v[32:47]
	v_mfma_f32_32x32x16_bf16 v[32:47], v[186:189], v[68:71], v[32:47]
	v_mfma_f32_32x32x16_bf16 v[32:47], v[206:209], v[76:79], v[32:47]
	v_mfma_f32_32x32x16_bf16 v[48:63], v[174:177], v[76:79], v[48:63]
	s_waitcnt lgkmcnt(1)
	v_mfma_f32_32x32x16_bf16 v[48:63], v[144:147], v[72:75], v[48:63]
	s_waitcnt lgkmcnt(0)
	v_mfma_f32_32x32x16_bf16 v[48:63], v[148:151], v[64:67], v[48:63]
	ds_read_b128 v[148:151], v230 offset:8800
	s_cbranch_vccnz .LBB0_800
	s_xor_b64 vcc, s[80:81], -1
	s_and_b64 s[82:83], vcc, s[82:83]
	v_readlane_b32 vcc_lo, v254, 49
	v_readlane_b32 vcc_hi, v254, 50
	s_mov_b32 s89, s91
	v_readlane_b32 s90, v254, 51
	s_and_b64 vcc, s[80:81], vcc
	v_readlane_b32 s91, v254, 52
	s_or_b64 vcc, s[78:79], vcc
	s_and_b64 s[90:91], s[82:83], s[90:91]
	s_or_b64 vcc, vcc, s[90:91]
	v_readlane_b32 s90, v254, 53
	v_cndmask_b32_e32 v48, v48, v240, vcc
	v_readlane_b32 s91, v254, 54
	v_readlane_b32 vcc_lo, v254, 55
	s_and_b64 s[90:91], s[80:81], s[90:91]
	v_readlane_b32 vcc_hi, v254, 56
	s_or_b64 s[90:91], s[78:79], s[90:91]
	s_and_b64 vcc, s[82:83], vcc
	s_or_b64 vcc, s[90:91], vcc
	v_readlane_b32 s90, v254, 57
	v_cndmask_b32_e32 v49, v49, v240, vcc
	v_readlane_b32 s91, v254, 58
	v_readlane_b32 vcc_lo, v254, 59
	s_and_b64 s[90:91], s[80:81], s[90:91]
	v_readlane_b32 vcc_hi, v254, 60
	s_or_b64 s[90:91], s[78:79], s[90:91]
	s_and_b64 vcc, s[82:83], vcc
	s_or_b64 vcc, s[90:91], vcc
	v_readlane_b32 s90, v254, 61
	v_cndmask_b32_e32 v50, v50, v240, vcc
	v_readlane_b32 s91, v254, 62
	v_readlane_b32 vcc_lo, v254, 63
	s_and_b64 s[90:91], s[80:81], s[90:91]
	v_readlane_b32 vcc_hi, v245, 0
	s_or_b64 s[90:91], s[78:79], s[90:91]
	s_and_b64 vcc, s[82:83], vcc
	s_or_b64 vcc, s[90:91], vcc
	v_readlane_b32 s90, v245, 1
	v_cndmask_b32_e32 v51, v51, v240, vcc
	v_readlane_b32 s91, v245, 2
	v_readlane_b32 vcc_lo, v245, 3
	s_and_b64 s[90:91], s[80:81], s[90:91]
	v_readlane_b32 vcc_hi, v245, 4
	s_or_b64 s[90:91], s[78:79], s[90:91]
	s_and_b64 vcc, s[82:83], vcc
	s_or_b64 vcc, s[90:91], vcc
	v_readlane_b32 s90, v245, 5
	v_cndmask_b32_e32 v52, v52, v240, vcc
	v_readlane_b32 s91, v245, 6
	v_readlane_b32 vcc_lo, v245, 7
	s_and_b64 s[90:91], s[80:81], s[90:91]
	v_readlane_b32 vcc_hi, v245, 8
	s_or_b64 s[90:91], s[78:79], s[90:91]
	s_and_b64 vcc, s[82:83], vcc
	s_or_b64 vcc, s[90:91], vcc
	v_readlane_b32 s90, v245, 9
	v_cndmask_b32_e32 v53, v53, v240, vcc
	v_readlane_b32 s91, v245, 10
	v_readlane_b32 vcc_lo, v245, 11
	s_and_b64 s[90:91], s[80:81], s[90:91]
	v_readlane_b32 vcc_hi, v245, 12
	s_or_b64 s[90:91], s[78:79], s[90:91]
	s_and_b64 vcc, s[82:83], vcc
	s_or_b64 vcc, s[90:91], vcc
	v_readlane_b32 s90, v245, 13
	v_cndmask_b32_e32 v54, v54, v240, vcc
	v_readlane_b32 s91, v245, 14
	v_readlane_b32 vcc_lo, v245, 15
	s_and_b64 s[90:91], s[80:81], s[90:91]
	v_readlane_b32 vcc_hi, v245, 16
	s_or_b64 s[90:91], s[78:79], s[90:91]
	s_and_b64 vcc, s[82:83], vcc
	s_or_b64 vcc, s[90:91], vcc
	v_readlane_b32 s90, v245, 17
	v_cndmask_b32_e32 v55, v55, v240, vcc
	v_readlane_b32 s91, v245, 18
	v_readlane_b32 vcc_lo, v245, 19
	s_and_b64 s[90:91], s[80:81], s[90:91]
	v_readlane_b32 vcc_hi, v245, 20
	s_or_b64 s[90:91], s[78:79], s[90:91]
	s_and_b64 vcc, s[82:83], vcc
	s_or_b64 vcc, s[90:91], vcc
	v_readlane_b32 s90, v245, 21
	v_cndmask_b32_e32 v56, v56, v240, vcc
	v_readlane_b32 s91, v245, 22
	v_readlane_b32 vcc_lo, v245, 23
	s_and_b64 s[90:91], s[80:81], s[90:91]
	v_readlane_b32 vcc_hi, v245, 24
	s_or_b64 s[90:91], s[78:79], s[90:91]
	s_and_b64 vcc, s[82:83], vcc
	s_or_b64 vcc, s[90:91], vcc
	v_readlane_b32 s90, v245, 25
	v_cndmask_b32_e32 v57, v57, v240, vcc
	v_readlane_b32 s91, v245, 26
; DI int crow(int i, int hf) { return (i & 3) + 8 * (i >> 2) + 4 * hf; }
; #define NSA_STORE(Kb, Vb) do { *(LAS v4u*)((Kb) + skey * PA + 8 * sch) = kreg; LAS unsigned* d0_ = (LAS unsigned*)((Vb) + (4 * sdg) * PV + vpos(2 * skp)); \
;         d0_[0] = (vr0.x & 0xffffu) | (vr1.x << 16); d0_[PV / 2] = (vr0.x >> 16) | (vr1.x & 0xffff0000u); d0_[PV] = (vr0.y & 0xffffu) | (vr1.y << 16); d0_[3 * PV / 2] = (vr0.y >> 16) | (vr1.y & 0xffff0000u); } while (0)
; DI void nsa_item(KA a, LAS unsigned char* lds, const int it) {
;     ...
;         if (mode != 0) {
; #pragma unroll
;             for (int kt = 0; kt < 2; ++kt)
; #pragma unroll
;                 for (int i2 = 0; i2 < 16; ++i2) { const int kl = 32 * kt + crow(i2, hf); const bool bad = rowoff || (mode == 1 && kl > tql) || (mode == 2 && kl <= tql); st[kt][i2] = bad ? -INFINITY : st[kt][i2]; }
;     ...
;         if (i + 1 < n) { if (i & 1) NSA_STORE(Kt, VT); else NSA_STORE(Kt1, VT1); if (i + 2 < n) NSA_LOAD(LIST[i + 2]); }
	v_readlane_b32 vcc_lo, v245, 27
	s_and_b64 s[90:91], s[80:81], s[90:91]
	v_readlane_b32 vcc_hi, v245, 28
	s_or_b64 s[90:91], s[78:79], s[90:91]
	s_and_b64 vcc, s[82:83], vcc
	s_or_b64 vcc, s[90:91], vcc
	v_readlane_b32 s90, v245, 29
	v_cndmask_b32_e32 v58, v58, v240, vcc
	v_readlane_b32 s91, v245, 30
	v_readlane_b32 vcc_lo, v245, 31
	s_and_b64 s[90:91], s[80:81], s[90:91]
	v_readlane_b32 vcc_hi, v245, 32
	s_or_b64 s[90:91], s[78:79], s[90:91]
	s_and_b64 vcc, s[82:83], vcc
	s_or_b64 vcc, s[90:91], vcc
	v_readlane_b32 s90, v245, 33
	v_cndmask_b32_e32 v59, v59, v240, vcc
	v_readlane_b32 s91, v245, 34
	v_readlane_b32 vcc_lo, v245, 35
	s_and_b64 s[90:91], s[80:81], s[90:91]
	v_readlane_b32 vcc_hi, v245, 36
	s_or_b64 s[90:91], s[78:79], s[90:91]
	s_and_b64 vcc, s[82:83], vcc
	s_or_b64 vcc, s[90:91], vcc
	s_and_b64 s[90:91], s[80:81], s[92:93]
	v_cndmask_b32_e32 v60, v60, v240, vcc
	s_or_b64 s[90:91], s[78:79], s[90:91]
	s_and_b64 vcc, s[82:83], s[94:95]
	s_or_b64 vcc, s[90:91], vcc
	s_and_b64 s[90:91], s[80:81], s[96:97]
	v_cndmask_b32_e32 v61, v61, v240, vcc
	s_or_b64 s[90:91], s[78:79], s[90:91]
	s_and_b64 vcc, s[82:83], s[6:7]
	s_or_b64 vcc, s[90:91], vcc
	s_and_b64 s[90:91], s[80:81], s[8:9]
	v_cndmask_b32_e32 v62, v62, v240, vcc
	s_or_b64 s[90:91], s[78:79], s[90:91]
	s_and_b64 vcc, s[82:83], s[10:11]
	s_or_b64 vcc, s[90:91], vcc
	s_and_b64 s[90:91], s[80:81], s[12:13]
	v_cndmask_b32_e32 v63, v63, v240, vcc
	s_or_b64 s[90:91], s[78:79], s[90:91]
	s_and_b64 vcc, s[82:83], s[14:15]
	s_or_b64 vcc, s[90:91], vcc
	s_and_b64 s[90:91], s[80:81], s[16:17]
	v_cndmask_b32_e32 v32, v32, v240, vcc
	s_or_b64 s[90:91], s[78:79], s[90:91]
	s_and_b64 vcc, s[82:83], s[18:19]
	s_or_b64 vcc, s[90:91], vcc
	s_and_b64 s[90:91], s[80:81], s[20:21]
	v_cndmask_b32_e32 v33, v33, v240, vcc
	s_or_b64 s[90:91], s[78:79], s[90:91]
	s_and_b64 vcc, s[82:83], s[22:23]
	s_or_b64 vcc, s[90:91], vcc
	s_and_b64 s[90:91], s[80:81], s[24:25]
	v_cndmask_b32_e32 v34, v34, v240, vcc
	s_or_b64 s[90:91], s[78:79], s[90:91]
	s_and_b64 vcc, s[82:83], s[26:27]
	s_or_b64 vcc, s[90:91], vcc
	s_and_b64 s[90:91], s[80:81], s[28:29]
	v_cndmask_b32_e32 v35, v35, v240, vcc
	s_or_b64 s[90:91], s[78:79], s[90:91]
	s_and_b64 vcc, s[82:83], s[30:31]
	s_or_b64 vcc, s[90:91], vcc
	s_and_b64 s[90:91], s[80:81], s[34:35]
	v_cndmask_b32_e32 v36, v36, v240, vcc
	s_or_b64 s[90:91], s[78:79], s[90:91]
	s_and_b64 vcc, s[82:83], s[36:37]
	s_or_b64 vcc, s[90:91], vcc
	s_and_b64 s[90:91], s[80:81], s[38:39]
	v_cndmask_b32_e32 v37, v37, v240, vcc
	s_or_b64 s[90:91], s[78:79], s[90:91]
	s_and_b64 vcc, s[82:83], s[4:5]
	s_or_b64 vcc, s[90:91], vcc
	s_and_b64 s[90:91], s[80:81], s[40:41]
	v_cndmask_b32_e32 v38, v38, v240, vcc
	s_or_b64 s[90:91], s[78:79], s[90:91]
	s_and_b64 vcc, s[82:83], s[2:3]
	s_or_b64 vcc, s[90:91], vcc
	s_and_b64 s[90:91], s[80:81], s[0:1]
	v_cndmask_b32_e32 v39, v39, v240, vcc
	s_or_b64 s[90:91], s[78:79], s[90:91]
	s_and_b64 vcc, s[82:83], s[42:43]
	s_or_b64 vcc, s[90:91], vcc
	s_and_b64 s[90:91], s[80:81], s[44:45]
	v_cndmask_b32_e32 v40, v40, v240, vcc
	s_or_b64 s[90:91], s[78:79], s[90:91]
	s_and_b64 vcc, s[82:83], s[46:47]
	s_or_b64 vcc, s[90:91], vcc
	s_and_b64 s[90:91], s[80:81], s[48:49]
	v_cndmask_b32_e32 v41, v41, v240, vcc
	s_or_b64 s[90:91], s[78:79], s[90:91]
	s_and_b64 vcc, s[82:83], s[50:51]
	s_or_b64 vcc, s[90:91], vcc
	s_and_b64 s[90:91], s[80:81], s[52:53]
	v_cndmask_b32_e32 v42, v42, v240, vcc
	s_or_b64 s[90:91], s[78:79], s[90:91]
	s_and_b64 vcc, s[82:83], s[54:55]
	s_or_b64 vcc, s[90:91], vcc
	s_and_b64 s[90:91], s[80:81], s[56:57]
	v_cndmask_b32_e32 v43, v43, v240, vcc
	s_or_b64 s[90:91], s[78:79], s[90:91]
	s_and_b64 vcc, s[82:83], s[58:59]
	s_or_b64 vcc, s[90:91], vcc
	s_and_b64 s[90:91], s[80:81], s[60:61]
	v_cndmask_b32_e32 v44, v44, v240, vcc
	s_or_b64 s[90:91], s[78:79], s[90:91]
	s_and_b64 vcc, s[82:83], s[62:63]
	s_or_b64 vcc, s[90:91], vcc
	s_and_b64 s[90:91], s[80:81], s[64:65]
	v_cndmask_b32_e32 v45, v45, v240, vcc
	s_or_b64 s[90:91], s[78:79], s[90:91]
	s_and_b64 vcc, s[82:83], s[66:67]
	s_and_b64 s[80:81], s[80:81], s[68:69]
	s_or_b64 vcc, s[90:91], vcc
	s_or_b64 s[78:79], s[78:79], s[80:81]
	s_and_b64 s[80:81], s[82:83], s[70:71]
	v_cndmask_b32_e32 v46, v46, v240, vcc
	s_or_b64 vcc, s[78:79], s[80:81]
	v_readlane_b32 s90, v254, 47
	s_mov_b32 s91, s89
	v_cndmask_b32_e32 v47, v47, v240, vcc
.LBB0_800:
	s_add_i32 s79, s87, 1
	s_cmp_ge_i32 s79, s84
	s_cbranch_scc1 .Lnsa_rsskip0
	s_waitcnt vmcnt(1)
	v_and_b32_e32 v89, 0xffff, v126
	v_lshrrev_b32_e32 v139, 16, v126
	s_mov_b32 s77, 0xffff0000
	v_and_b32_e32 v140, 0xffff, v127
	v_lshrrev_b32_e32 v143, 16, v127
	s_waitcnt vmcnt(0)
	v_lshl_or_b32 v89, v128, 16, v89
	v_and_or_b32 v139, v128, s77, v139
	v_lshl_or_b32 v140, v129, 16, v140
	v_and_or_b32 v143, v129, s77, v143
	s_andn2_b64 vcc, exec, s[74:75]
	s_mov_b64 s[74:75], -1
	s_cbranch_vccz .Lnsa_rs809
	s_andn2_b64 vcc, exec, s[74:75]
	s_cbranch_vccz .Lnsa_rs810

; #define NSA_STORE(Kb, Vb) do { *(LAS v4u*)((Kb) + skey * PA + 8 * sch) = kreg; LAS unsigned* d0_ = (LAS unsigned*)((Vb) + (4 * sdg) * PV + vpos(2 * skp)); \
;         d0_[0] = (vr0.x & 0xffffu) | (vr1.x << 16); d0_[PV / 2] = (vr0.x >> 16) | (vr1.x & 0xffff0000u); d0_[PV] = (vr0.y & 0xffffu) | (vr1.y << 16); d0_[3 * PV / 2] = (vr0.y >> 16) | (vr1.y & 0xffff0000u); } while (0)
; DI void nsa_item(KA a, LAS unsigned char* lds, const int it) {
;     ...
;         if (i + 1 < n) { if (i & 1) NSA_STORE(Kt, VT); else NSA_STORE(Kt1, VT1); if (i + 2 < n) NSA_LOAD(LIST[i + 2]); }
.Lnsa_rs806:
	v_mov_b32_e32 v80, v250
	s_movk_i32 s75, 0xbb0
	s_movk_i32 s79, 0x1c00
	v_lshlrev_b32_e32 v81, 6, v80
	v_readfirstlane_b32 s74, v80
	v_and_b32_e32 v80, 0x3fc0, v81
	s_cmpk_lt_u32 s74, 0x100
	v_readlane_b32 s74, v254, 48
	s_cselect_b32 s75, s75, 0xcb0
	s_nop 0
	v_add_u32_e32 v89, s74, v80
	s_movk_i32 s74, 0xb30
	s_cselect_b32 s74, s74, 0xc30
	s_or_b32 s77, s74, s33
	s_or_b32 s78, s75, s33
	v_readlane_b32 s74, v254, 39
	v_readlane_b32 s75, v254, 40
	v_add_u32_e32 v82, v89, v132
	s_lshl_b32 s90, s77, 1
	v_mov_b64_e32 v[80:81], s[74:75]
	v_mad_i64_i32 v[82:83], s[74:75], v82, s79, v[80:81]
	v_add_u32_e32 v89, v89, v133
	v_lshl_add_u64 v[82:83], v[82:83], 0, s[90:91]
	v_mad_i64_i32 v[80:81], s[74:75], v89, s79, v[80:81]
	s_lshl_b32 s90, s78, 1
	v_lshl_add_u64 v[80:81], v[80:81], 0, s[90:91]
	v_mov_b32_e32 v89, v193
	v_lshl_add_u64 v[82:83], v[82:83], 0, v[192:193]
	v_lshl_add_u64 v[128:129], v[80:81], 0, v[88:89]
	global_load_dwordx4 v[80:83], v[82:83], off
	s_nop 0
	global_load_dwordx2 v[126:127], v[128:129], off
	v_add_co_u32_e32 v128, vcc, 0x1000, v128
	v_readlane_b32 s90, v254, 47
	s_nop 0
	v_addc_co_u32_e32 v129, vcc, 0, v129, vcc
	global_load_dwordx2 v[128:129], v[128:129], off offset:3072
	s_branch .Lnsa_rsdone

; DI void nsa_item(KA a, LAS unsigned char* lds, const int it) {
;     ...
;         float mx = -INFINITY;
; #pragma unroll
;         for (int kt = 0; kt < 2; ++kt)
; #pragma unroll
;             for (int i2 = 0; i2 < 16; ++i2) mx = fmaxf(mx, st[kt][i2]);
;         mx = fmaxf(mx, __shfl_xor(mx, 32));
;         const bool drift = (fabsf(mx) > 24.f) && (mx > -INFINITY);
;         if (__any(drift)) {
;             const float d = drift ? mx : 0.f, scl = __builtin_amdgcn_exp2f(-d); m_ref += d; l_run *= scl; ot[0] = ot[0] * scl; ot[1] = ot[1] * scl;
; #pragma unroll
;             for (int kt = 0; kt < 2; ++kt)
; #pragma unroll
;                 for (int i2 = 0; i2 < 16; ++i2) st[kt][i2] -= d;
;         }
.Lnsa_rsdone:
	s_add_i32 s87, s87, -2
.Lnsa_rsskip:
	s_mov_b32 s80, 0xff800000
	v_max3_f32 v89, v48, s80, v49
	v_max3_f32 v89, v89, v50, v51
	v_max3_f32 v89, v89, v52, v53
	v_max3_f32 v89, v89, v54, v55
	v_max3_f32 v89, v89, v56, v57
	v_max3_f32 v89, v89, v58, v59
	v_max3_f32 v89, v89, v60, v61
	v_max3_f32 v89, v89, v62, v63
	s_nop 1
	v_max3_f32 v89, v89, v32, v33
	v_max3_f32 v89, v89, v34, v35
	v_max3_f32 v89, v89, v36, v37
	v_max3_f32 v89, v89, v38, v39
	v_max3_f32 v89, v89, v40, v41
	v_max3_f32 v89, v89, v42, v43
	v_max3_f32 v89, v89, v44, v45
	v_max3_f32 v89, v89, v46, v47
	v_mov_b32_e32 v139, v89
	s_mov_b32 s78, 0x41c00000
	s_movk_i32 s81, 0x1ff
	s_nop 1
	v_permlane32_swap_b32_e32 v139, v89
	v_max_f32_e32 v89, v89, v139
	v_cmp_gt_f32_e64 s[78:79], |v89|, s78
	v_cmp_lg_f32_e32 vcc, s80, v89
	s_and_b64 vcc, vcc, s[78:79]
	s_cbranch_vccz .LBB0_802
	v_cndmask_b32_e32 v140, 0, v89, vcc
	v_exp_f32_e64 v144, -v140
	v_add_f32_e32 v137, v137, v140
	v_pk_add_f32 v[48:49], v[48:49], v[140:141] op_sel_hi:[1,0] neg_lo:[0,1] neg_hi:[0,1]
	v_pk_add_f32 v[50:51], v[50:51], v[140:141] op_sel_hi:[1,0] neg_lo:[0,1] neg_hi:[0,1]
	v_pk_mul_f32 v[30:31], v[30:31], v[144:145] op_sel_hi:[1,0]
	v_pk_mul_f32 v[28:29], v[28:29], v[144:145] op_sel_hi:[1,0]
	v_pk_mul_f32 v[26:27], v[26:27], v[144:145] op_sel_hi:[1,0]
	v_pk_mul_f32 v[24:25], v[24:25], v[144:145] op_sel_hi:[1,0]
	v_pk_mul_f32 v[22:23], v[22:23], v[144:145] op_sel_hi:[1,0]
	v_pk_mul_f32 v[20:21], v[20:21], v[144:145] op_sel_hi:[1,0]
	v_pk_mul_f32 v[18:19], v[18:19], v[144:145] op_sel_hi:[1,0]
	v_pk_mul_f32 v[16:17], v[16:17], v[144:145] op_sel_hi:[1,0]
	v_pk_mul_f32 v[14:15], v[14:15], v[144:145] op_sel_hi:[1,0]
	v_pk_mul_f32 v[12:13], v[12:13], v[144:145] op_sel_hi:[1,0]
	v_pk_mul_f32 v[10:11], v[10:11], v[144:145] op_sel_hi:[1,0]
	v_pk_mul_f32 v[8:9], v[8:9], v[144:145] op_sel_hi:[1,0]
	v_pk_mul_f32 v[6:7], v[6:7], v[144:145] op_sel_hi:[1,0]
	v_pk_mul_f32 v[4:5], v[4:5], v[144:145] op_sel_hi:[1,0]
	v_pk_mul_f32 v[2:3], v[2:3], v[144:145] op_sel_hi:[1,0]
	v_pk_mul_f32 v[0:1], v[0:1], v[144:145] op_sel_hi:[1,0]
	v_pk_add_f32 v[52:53], v[52:53], v[140:141] op_sel_hi:[1,0] neg_lo:[0,1] neg_hi:[0,1]
	v_pk_add_f32 v[54:55], v[54:55], v[140:141] op_sel_hi:[1,0] neg_lo:[0,1] neg_hi:[0,1]
	v_pk_add_f32 v[56:57], v[56:57], v[140:141] op_sel_hi:[1,0] neg_lo:[0,1] neg_hi:[0,1]
	v_pk_add_f32 v[58:59], v[58:59], v[140:141] op_sel_hi:[1,0] neg_lo:[0,1] neg_hi:[0,1]
	v_pk_add_f32 v[60:61], v[60:61], v[140:141] op_sel_hi:[1,0] neg_lo:[0,1] neg_hi:[0,1]
	v_pk_add_f32 v[62:63], v[62:63], v[140:141] op_sel_hi:[1,0] neg_lo:[0,1] neg_hi:[0,1]
	v_pk_add_f32 v[32:33], v[32:33], v[140:141] op_sel_hi:[1,0] neg_lo:[0,1] neg_hi:[0,1]
	v_pk_add_f32 v[34:35], v[34:35], v[140:141] op_sel_hi:[1,0] neg_lo:[0,1] neg_hi:[0,1]
	v_pk_add_f32 v[36:37], v[36:37], v[140:141] op_sel_hi:[1,0] neg_lo:[0,1] neg_hi:[0,1]
	v_pk_add_f32 v[38:39], v[38:39], v[140:141] op_sel_hi:[1,0] neg_lo:[0,1] neg_hi:[0,1]
	v_pk_add_f32 v[40:41], v[40:41], v[140:141] op_sel_hi:[1,0] neg_lo:[0,1] neg_hi:[0,1]
	v_pk_add_f32 v[42:43], v[42:43], v[140:141] op_sel_hi:[1,0] neg_lo:[0,1] neg_hi:[0,1]
	v_pk_add_f32 v[44:45], v[44:45], v[140:141] op_sel_hi:[1,0] neg_lo:[0,1] neg_hi:[0,1]
	v_pk_add_f32 v[46:47], v[46:47], v[140:141] op_sel_hi:[1,0] neg_lo:[0,1] neg_hi:[0,1]
	v_mul_f32_e32 v135, v135, v144
; DI f32x16 mma32(bf16x8 a, bf16x8 b, f32x16 c) { return __builtin_amdgcn_mfma_f32_32x32x16_bf16(a, b, c, 0, 0, 0); }
; DI bf16x8 packp(const f32x16& x, const int h8) { v4u p; p.x = pk2(x[h8 + 0], x[h8 + 1]); p.y = pk2(x[h8 + 2], x[h8 + 3]); p.z = pk2(x[h8 + 4], x[h8 + 5]); p.w = pk2(x[h8 + 6], x[h8 + 7]); return __builtin_bit_cast(bf16x8, p); }
; #define NSA_STORE(Kb, Vb) do { *(LAS v4u*)((Kb) + skey * PA + 8 * sch) = kreg; LAS unsigned* d0_ = (LAS unsigned*)((Vb) + (4 * sdg) * PV + vpos(2 * skp)); \
;         d0_[0] = (vr0.x & 0xffffu) | (vr1.x << 16); d0_[PV / 2] = (vr0.x >> 16) | (vr1.x & 0xffff0000u); d0_[PV] = (vr0.y & 0xffffu) | (vr1.y << 16); d0_[3 * PV / 2] = (vr0.y >> 16) | (vr1.y & 0xffff0000u); } while (0)
; DI void nsa_item(KA a, LAS unsigned char* lds, const int it) {
;     ...
;         f32x2 ls2 = {0.f, 0.f};
; #pragma unroll
;         for (int kt = 0; kt < 2; ++kt)
; #pragma unroll
;             for (int i2 = 0; i2 < 16; i2 += 2) { const float p0 = __builtin_amdgcn_exp2f(st[kt][i2]), p1 = __builtin_amdgcn_exp2f(st[kt][i2 + 1]); st[kt][i2] = p0; st[kt][i2 + 1] = p1; ls2 += (f32x2){p0, p1}; }
;         l_run += ls2[0] + ls2[1];
; #pragma unroll
;         for (int sp = 0; sp < 4; ++sp) { const bf16x8 pf = packp(st[sp >> 1], 8 * (sp & 1));
; #pragma unroll
;             for (int dh = 0; dh < 2; ++dh) ot[dh] = mma32(vfrag(Vc, 32 * dh + r, sp, hf), pf, ot[dh]); }
;         if (i + 1 < n) { if (i & 1) NSA_STORE(Kt, VT); else NSA_STORE(Kt1, VT1); if (i + 2 < n) NSA_LOAD(LIST[i + 2]); }
;         __syncthreads();
;     }
.LBB0_802:
	s_waitcnt lgkmcnt(0)
	s_barrier
	s_bitcmp1_b32 s87, 0
	s_cselect_b32 s74, 0, 0x9000
	s_movk_i32 s75, 0x4800
	s_cselect_b32 s75, s75, 0xb400
	v_add3_u32 v231, s74, v90, v130
	v_add3_u32 v230, s75, v90, v131
	ds_read_b128 v[170:173], v231 offset:64
	ds_read_b128 v[178:181], v231 offset:4608
	ds_read_b128 v[182:185], v231 offset:4640
	ds_read_b128 v[186:189], v231 offset:4672
	ds_read_b128 v[206:209], v231 offset:4704
	ds_read_b128 v[174:177], v231 offset:96
	v_exp_f32_e32 v48, v48
	v_exp_f32_e32 v49, v49
	v_exp_f32_e32 v50, v50
	v_exp_f32_e32 v51, v51
	v_exp_f32_e32 v52, v52
	v_exp_f32_e32 v53, v53
	v_exp_f32_e32 v54, v54
	v_exp_f32_e32 v55, v55
	v_cvt_pk_bf16_f32 v144, v48, v49
	v_cvt_pk_bf16_f32 v145, v50, v51
	v_cvt_pk_bf16_f32 v146, v52, v53
	v_cvt_pk_bf16_f32 v147, v54, v55
	v_exp_f32_e32 v56, v56
	v_exp_f32_e32 v57, v57
	s_nop 0
	v_mfma_f32_32x32x16_bf16 v[16:31], v[210:213], v[144:147], v[16:31]
	v_exp_f32_e32 v58, v58
	v_exp_f32_e32 v59, v59
	v_exp_f32_e32 v60, v60
	v_exp_f32_e32 v61, v61
	v_exp_f32_e32 v62, v62
	v_exp_f32_e32 v63, v63
	s_nop 0
	v_mfma_f32_32x32x16_bf16 v[0:15], v[218:221], v[144:147], v[0:15]
	v_cvt_pk_bf16_f32 v144, v56, v57
	v_cvt_pk_bf16_f32 v145, v58, v59
	v_cvt_pk_bf16_f32 v146, v60, v61
	v_cvt_pk_bf16_f32 v147, v62, v63
	v_exp_f32_e32 v32, v32
	v_exp_f32_e32 v33, v33
	s_nop 0
	v_mfma_f32_32x32x16_bf16 v[0:15], v[222:225], v[144:147], v[0:15]
	v_exp_f32_e32 v34, v34
	v_exp_f32_e32 v35, v35
	v_exp_f32_e32 v36, v36
	v_exp_f32_e32 v37, v37
	v_exp_f32_e32 v38, v38
	v_exp_f32_e32 v39, v39
	v_mfma_f32_32x32x16_bf16 v[16:31], v[214:217], v[144:147], v[16:31]
	v_cvt_pk_bf16_f32 v144, v32, v33
	v_cvt_pk_bf16_f32 v145, v34, v35
	v_cvt_pk_bf16_f32 v146, v36, v37
	v_cvt_pk_bf16_f32 v147, v38, v39
	v_exp_f32_e32 v40, v40
	v_exp_f32_e32 v41, v41
	v_exp_f32_e32 v42, v42
	s_nop 0
	v_mfma_f32_32x32x16_bf16 v[16:31], v[226:229], v[144:147], v[16:31]
	v_exp_f32_e32 v43, v43
	v_exp_f32_e32 v44, v44
	v_exp_f32_e32 v45, v45
	v_exp_f32_e32 v46, v46
	v_exp_f32_e32 v47, v47
	s_add_i32 s76, s87, 1
	s_nop 0
	v_mfma_f32_32x32x16_bf16 v[0:15], v[152:155], v[144:147], v[0:15]
	v_cvt_pk_bf16_f32 v144, v40, v41
	v_cvt_pk_bf16_f32 v145, v42, v43
	v_cvt_pk_bf16_f32 v146, v44, v45
	v_cvt_pk_bf16_f32 v147, v46, v47
	s_cmp_ge_i32 s76, s84
	s_nop 0
	v_mfma_f32_32x32x16_bf16 v[16:31], v[246:249], v[144:147], v[16:31]
	s_nop 0
	v_mfma_f32_32x32x16_bf16 v[0:15], v[148:151], v[144:147], v[0:15]
.LBB0_807:
	s_add_i32 s86, s86, 4
	s_add_i32 s74, s86, -8
	v_mov_b32_e32 v191, s74
	ds_read_b32 v191, v191
	v_mov_b32_e32 v250, s86
	ds_read_b32 v250, v250
	ds_read_b128 v[210:213], v230
	ds_read_b128 v[218:221], v230 offset:8704
	ds_read_b128 v[222:225], v230 offset:8736
	ds_read_b128 v[214:217], v230 offset:32
	ds_read_b128 v[226:229], v230 offset:64
	ds_read_b128 v[152:155], v230 offset:8768
	ds_read_b128 v[246:249], v230 offset:96
	ds_read_b128 v[144:147], v231
	ds_read_b128 v[148:151], v231 offset:32
	v_pk_add_f32 v[48:49], v[48:49], v[50:51]
	v_pk_add_f32 v[52:53], v[52:53], v[54:55]
	v_pk_add_f32 v[56:57], v[56:57], v[58:59]
	v_pk_add_f32 v[60:61], v[60:61], v[62:63]
	v_pk_add_f32 v[32:33], v[32:33], v[34:35]
	v_pk_add_f32 v[36:37], v[36:37], v[38:39]
	v_pk_add_f32 v[40:41], v[40:41], v[42:43]
	v_pk_add_f32 v[44:45], v[44:45], v[46:47]
	v_pk_add_f32 v[48:49], v[48:49], v[52:53]
	v_pk_add_f32 v[56:57], v[56:57], v[60:61]
	v_pk_add_f32 v[32:33], v[32:33], v[36:37]
	v_pk_add_f32 v[40:41], v[40:41], v[44:45]
	s_cmp_lg_u32 s84, s76
	v_pk_add_f32 v[48:49], v[48:49], v[56:57]
	v_pk_add_f32 v[32:33], v[32:33], v[40:41]
	s_nop 0
	v_pk_add_f32 v[32:33], v[32:33], v[48:49]
	s_nop 0
	v_add_f32_e32 v32, v32, v33
	v_add_f32_e32 v135, v135, v32
	s_cbranch_scc0 .Lnsa_rot_exit
	s_mov_b32 s87, s76
	s_branch .LBB0_796

; #define NSA_STORE(Kb, Vb) do { *(LAS v4u*)((Kb) + skey * PA + 8 * sch) = kreg; LAS unsigned* d0_ = (LAS unsigned*)((Vb) + (4 * sdg) * PV + vpos(2 * skp)); \
;         d0_[0] = (vr0.x & 0xffffu) | (vr1.x << 16); d0_[PV / 2] = (vr0.x >> 16) | (vr1.x & 0xffff0000u); d0_[PV] = (vr0.y & 0xffffu) | (vr1.y << 16); d0_[3 * PV / 2] = (vr0.y >> 16) | (vr1.y & 0xffff0000u); } while (0)
; DI void nsa_item(KA a, LAS unsigned char* lds, const int it) {
;     ...
;         if (i + 1 < n) { if (i & 1) NSA_STORE(Kt, VT); else NSA_STORE(Kt1, VT1); if (i + 2 < n) NSA_LOAD(LIST[i + 2]); }
.Lnsa_rsskip0:
	s_nop 7
	s_branch .Lnsa_rsskip
